# FFN-in K-loop without per-phase s_setprio toggling
# baseline (speedup 1.0000x reference)
; #define PG8_STAGE(bufoff, gbase, voff) do { _Pragma("unroll") for (int _i = 0; _i < 2; ++_i) \
;         __builtin_amdgcn_global_load_lds((const unsigned*)((const char*)(gbase) + (voff)[_i]), (LAS unsigned*)(lds + (bufoff) + ldsw + _i * 8192), 16, 0, 0); } while (0)
; #define PG8_LDA(dst, b, h) do { _Pragma("unroll") for (int m = 0; m < 4; ++m) _Pragma("unroll") for (int k = 0; k < 2; ++k) dst[m][k] = *(const LAS bf16x8*)(lds + PG8_SA(b, h) + aoff + m * 2048 + k * 1024); } while (0)
; #define PG8_LDB(dst, b, h) do { _Pragma("unroll") for (int n = 0; n < 2; ++n) _Pragma("unroll") for (int k = 0; k < 2; ++k) dst[n][k] = *(const LAS bf16x8*)(lds + PG8_SB(b, h) + boff + n * 2048 + k * 1024); } while (0)
; #define PG8_MMA(ai, bj, At, Bt) do { __builtin_amdgcn_s_setprio(1); _Pragma("unroll") for (int m = 0; m < 4; ++m) _Pragma("unroll") for (int n = 0; n < 2; ++n) _Pragma("unroll") for (int k = 0; k < 2; ++k) \
;         acc[ai][bj][m][n] = __builtin_amdgcn_mfma_f32_16x16x32_bf16(Bt[n][k], At[m][k], acc[ai][bj][m][n], 0, 0, 0); __builtin_amdgcn_s_setprio(0); } while (0)
; #define PG8_WAIT_V(n) asm volatile("s_waitcnt vmcnt(" #n ")" ::: "memory")
; #define PG8_WAIT_L(n) asm volatile("s_waitcnt lgkmcnt(" #n ")" ::: "memory")
; #define PG8_BAR __builtin_amdgcn_s_barrier()
; #define PG8_SCHED __builtin_amdgcn_sched_barrier(0)
; template <class Epi>
; __device__ __forceinline__ void gemm_phase(LAS unsigned char* lds, const Gemm g, const StaticOrder& S, const Epi& E, const int tid_in) {
;     ...
;         for (int t = 0; t < nt; t += 2) {
;             const bool last = (t == nt - 2);
;             const char* a1 = cA + (size_t)(t + 1) * kstep;
;             const char* a2 = last ? nA : cA + (size_t)(t + 2) * kstep; const char* b2 = last ? nB : cB + (size_t)(t + 2) * kstep;
;             const char* a3 = a2 + kstep; const char* b3 = b2 + kstep;
;             PG8_LDB(B0, 0, 0); PG8_LDB(B1, 0, 1); PG8_SCHED; PG8_LDA(At, 0, 0); PG8_STAGE(PG8_SA(1, 1), a1 + hstepA, voffA);
;             PG8_WAIT_V(8); PG8_WAIT_L(0); PG8_BAR; PG8_MMA(0, 0, At, B0); PG8_MMA(0, 1, At, B1); PG8_BAR; PG8_SCHED;
;             PG8_LDA(At, 0, 1); PG8_STAGE(PG8_SB(0, 0), b2, voffB); PG8_STAGE(PG8_SB(0, 1), b2 + hstepB, voffB); PG8_STAGE(PG8_SA(0, 0), a2, voffA);
;             PG8_WAIT_V(8); PG8_WAIT_L(0); PG8_BAR; PG8_MMA(1, 0, At, B0); PG8_MMA(1, 1, At, B1); PG8_BAR; PG8_SCHED;
.LBB0_232:
	s_add_u32 s20, s36, 0xfffc0080
	s_addc_u32 s21, s37, -1
	s_add_i32 s57, 0, 0x10000
	s_cmp_eq_u32 s56, 12
	s_cselect_b32 s21, s7, s21
	s_cselect_b32 s20, s17, s20
	s_cselect_b32 s35, s48, s39
	s_cselect_b32 s34, s50, s38
	s_add_i32 s58, 0, 0x14000
	v_add_u32_e32 v44, s57, v163
	v_add_u32_e32 v160, s58, v163
	ds_read_b128 v[32:35], v44
	ds_read_b128 v[36:39], v44 offset:1024
	ds_read_b128 v[40:43], v44 offset:2048
	ds_read_b128 v[44:47], v44 offset:3072
	ds_read_b128 v[168:171], v160
	ds_read_b128 v[172:175], v160 offset:1024
	ds_read_b128 v[176:179], v160 offset:2048
	ds_read_b128 v[180:183], v160 offset:3072
	v_lshl_add_u64 v[160:161], s[36:37], 0, v[156:157]
	s_add_i32 m0, s46, 0xc000
	ds_read_b128 v[184:187], v167
	ds_read_b128 v[188:191], v167 offset:1024
	ds_read_b128 v[192:195], v167 offset:2048
	ds_read_b128 v[196:199], v167 offset:3072
	ds_read_b128 v[200:203], v167 offset:4096
	ds_read_b128 v[204:207], v167 offset:5120
	ds_read_b128 v[208:211], v167 offset:6144
	ds_read_b128 v[212:215], v167 offset:7168
	global_load_lds_dwordx4 v[160:161], off
	v_lshl_add_u64 v[160:161], s[36:37], 0, v[158:159]
	s_add_i32 m0, s46, 0xe000
	s_nop 0
	global_load_lds_dwordx4 v[160:161], off
	s_waitcnt vmcnt(8)
	s_waitcnt lgkmcnt(0)
	s_barrier
	s_waitcnt lgkmcnt(0)
	v_mfma_f32_16x16x32_bf16 v[142:145], v[32:35], v[184:187], v[142:145]
	v_mfma_f32_16x16x32_bf16 v[138:141], v[40:43], v[184:187], v[138:141]
	v_mfma_f32_16x16x32_bf16 v[124:127], v[32:35], v[192:195], v[124:127]
	v_mfma_f32_16x16x32_bf16 v[120:123], v[40:43], v[192:195], v[120:123]
	v_mfma_f32_16x16x32_bf16 v[108:111], v[32:35], v[200:203], v[108:111]
	v_mfma_f32_16x16x32_bf16 v[104:107], v[40:43], v[200:203], v[104:107]
	v_mfma_f32_16x16x32_bf16 v[92:95], v[32:35], v[208:211], v[92:95]
	v_mfma_f32_16x16x32_bf16 v[88:91], v[40:43], v[208:211], v[88:91]
	v_mfma_f32_16x16x32_bf16 v[142:145], v[36:39], v[188:191], v[142:145]
	v_mfma_f32_16x16x32_bf16 v[138:141], v[44:47], v[188:191], v[138:141]
	v_mfma_f32_16x16x32_bf16 v[124:127], v[36:39], v[196:199], v[124:127]
	v_mfma_f32_16x16x32_bf16 v[120:123], v[44:47], v[196:199], v[120:123]
	v_mfma_f32_16x16x32_bf16 v[108:111], v[36:39], v[204:207], v[108:111]
	v_mfma_f32_16x16x32_bf16 v[104:107], v[44:47], v[204:207], v[104:107]
	v_mfma_f32_16x16x32_bf16 v[92:95], v[36:39], v[212:215], v[92:95]
	v_mfma_f32_16x16x32_bf16 v[88:91], v[44:47], v[212:215], v[88:91]
	v_mfma_f32_16x16x32_bf16 v[134:137], v[168:171], v[184:187], v[134:137]
	v_mfma_f32_16x16x32_bf16 v[130:133], v[176:179], v[184:187], v[130:133]
	v_mfma_f32_16x16x32_bf16 v[116:119], v[168:171], v[192:195], v[116:119]
	v_mfma_f32_16x16x32_bf16 v[112:115], v[176:179], v[192:195], v[112:115]
	v_mfma_f32_16x16x32_bf16 v[100:103], v[168:171], v[200:203], v[100:103]
	v_mfma_f32_16x16x32_bf16 v[96:99], v[176:179], v[200:203], v[96:99]
	v_mfma_f32_16x16x32_bf16 v[84:87], v[168:171], v[208:211], v[84:87]
	v_mfma_f32_16x16x32_bf16 v[80:83], v[176:179], v[208:211], v[80:83]
	v_mfma_f32_16x16x32_bf16 v[134:137], v[172:175], v[188:191], v[134:137]
	v_mfma_f32_16x16x32_bf16 v[130:133], v[180:183], v[188:191], v[130:133]
	v_mfma_f32_16x16x32_bf16 v[116:119], v[172:175], v[196:199], v[116:119]
	v_mfma_f32_16x16x32_bf16 v[112:115], v[180:183], v[196:199], v[112:115]
	v_mfma_f32_16x16x32_bf16 v[100:103], v[172:175], v[204:207], v[100:103]
	v_mfma_f32_16x16x32_bf16 v[96:99], v[180:183], v[204:207], v[96:99]
	v_mfma_f32_16x16x32_bf16 v[84:87], v[172:175], v[212:215], v[84:87]
	v_mfma_f32_16x16x32_bf16 v[80:83], v[180:183], v[212:215], v[80:83]
	s_barrier
	s_add_i32 s57, s57, s45
	v_lshl_add_u64 v[160:161], s[34:35], 0, v[148:149]
	s_mov_b32 m0, s57
	ds_read_b128 v[184:187], v167 offset:16384
	ds_read_b128 v[188:191], v167 offset:17408
	ds_read_b128 v[192:195], v167 offset:18432
	ds_read_b128 v[196:199], v167 offset:19456
	ds_read_b128 v[200:203], v167 offset:20480
	ds_read_b128 v[204:207], v167 offset:21504
	ds_read_b128 v[208:211], v167 offset:22528
	ds_read_b128 v[212:215], v167 offset:23552
	global_load_lds_dwordx4 v[160:161], off
	s_add_i32 m0, s57, 0x2000
	s_add_u32 s60, s34, 0x40000
	v_lshl_add_u64 v[216:217], s[34:35], 0, v[152:153]
	s_addc_u32 s61, s35, 0
	s_add_i32 s57, s58, s45
	global_load_lds_dwordx4 v[216:217], off
	v_lshl_add_u64 v[218:219], s[60:61], 0, v[148:149]
	s_mov_b32 m0, s57
	v_lshl_add_u64 v[220:221], s[20:21], 0, v[150:151]
	global_load_lds_dwordx4 v[218:219], off
	v_lshl_add_u64 v[218:219], s[60:61], 0, v[152:153]
	s_add_i32 m0, s57, 0x2000
	s_nop 0
	global_load_lds_dwordx4 v[218:219], off
	v_lshl_add_u64 v[218:219], s[20:21], 0, v[146:147]
	s_mov_b32 m0, s46
	s_nop 0
	global_load_lds_dwordx4 v[218:219], off
	s_mov_b32 m0, s47
	s_nop 0
	global_load_lds_dwordx4 v[220:221], off
	s_waitcnt vmcnt(8)
	s_waitcnt lgkmcnt(0)
	s_barrier
; #define PG8_STAGE(bufoff, gbase, voff) do { _Pragma("unroll") for (int _i = 0; _i < 2; ++_i) \
;         __builtin_amdgcn_global_load_lds((const unsigned*)((const char*)(gbase) + (voff)[_i]), (LAS unsigned*)(lds + (bufoff) + ldsw + _i * 8192), 16, 0, 0); } while (0)
; #define PG8_LDA(dst, b, h) do { _Pragma("unroll") for (int m = 0; m < 4; ++m) _Pragma("unroll") for (int k = 0; k < 2; ++k) dst[m][k] = *(const LAS bf16x8*)(lds + PG8_SA(b, h) + aoff + m * 2048 + k * 1024); } while (0)
; #define PG8_LDB(dst, b, h) do { _Pragma("unroll") for (int n = 0; n < 2; ++n) _Pragma("unroll") for (int k = 0; k < 2; ++k) dst[n][k] = *(const LAS bf16x8*)(lds + PG8_SB(b, h) + boff + n * 2048 + k * 1024); } while (0)
; #define PG8_MMA(ai, bj, At, Bt) do { __builtin_amdgcn_s_setprio(1); _Pragma("unroll") for (int m = 0; m < 4; ++m) _Pragma("unroll") for (int n = 0; n < 2; ++n) _Pragma("unroll") for (int k = 0; k < 2; ++k) \
;         acc[ai][bj][m][n] = __builtin_amdgcn_mfma_f32_16x16x32_bf16(Bt[n][k], At[m][k], acc[ai][bj][m][n], 0, 0, 0); __builtin_amdgcn_s_setprio(0); } while (0)
; #define PG8_WAIT_V(n) asm volatile("s_waitcnt vmcnt(" #n ")" ::: "memory")
; #define PG8_WAIT_L(n) asm volatile("s_waitcnt lgkmcnt(" #n ")" ::: "memory")
; #define PG8_BAR __builtin_amdgcn_s_barrier()
; #define PG8_SCHED __builtin_amdgcn_sched_barrier(0)
; template <class Epi>
; __device__ __forceinline__ void gemm_phase(LAS unsigned char* lds, const Gemm g, const StaticOrder& S, const Epi& E, const int tid_in) {
;     ...
;             PG8_WAIT_V(8); PG8_WAIT_L(0); PG8_BAR; PG8_MMA(1, 0, At, B0); PG8_MMA(1, 1, At, B1); PG8_BAR; PG8_SCHED;
;             PG8_LDB(B0, 1, 0); PG8_LDB(B1, 1, 1); PG8_SCHED; PG8_LDA(At, 1, 0); PG8_STAGE(PG8_SA(0, 1), a2 + hstepA, voffA);
;             PG8_WAIT_V(8); PG8_WAIT_L(0); PG8_BAR; PG8_MMA(0, 0, At, B0); PG8_MMA(0, 1, At, B1); PG8_BAR; PG8_SCHED;
	s_waitcnt lgkmcnt(0)
	v_mfma_f32_16x16x32_bf16 v[76:79], v[32:35], v[184:187], v[76:79]
	v_mfma_f32_16x16x32_bf16 v[72:75], v[40:43], v[184:187], v[72:75]
	v_mfma_f32_16x16x32_bf16 v[60:63], v[32:35], v[192:195], v[60:63]
	v_mfma_f32_16x16x32_bf16 v[56:59], v[40:43], v[192:195], v[56:59]
	v_mfma_f32_16x16x32_bf16 v[28:31], v[32:35], v[200:203], v[28:31]
	v_mfma_f32_16x16x32_bf16 v[24:27], v[40:43], v[200:203], v[24:27]
	v_mfma_f32_16x16x32_bf16 v[12:15], v[32:35], v[208:211], v[12:15]
	v_mfma_f32_16x16x32_bf16 v[8:11], v[40:43], v[208:211], v[8:11]
	v_mfma_f32_16x16x32_bf16 v[76:79], v[36:39], v[188:191], v[76:79]
	v_mfma_f32_16x16x32_bf16 v[72:75], v[44:47], v[188:191], v[72:75]
	v_mfma_f32_16x16x32_bf16 v[60:63], v[36:39], v[196:199], v[60:63]
	v_mfma_f32_16x16x32_bf16 v[56:59], v[44:47], v[196:199], v[56:59]
	v_mfma_f32_16x16x32_bf16 v[28:31], v[36:39], v[204:207], v[28:31]
	v_mfma_f32_16x16x32_bf16 v[24:27], v[44:47], v[204:207], v[24:27]
	v_mfma_f32_16x16x32_bf16 v[12:15], v[36:39], v[212:215], v[12:15]
	v_mfma_f32_16x16x32_bf16 v[8:11], v[44:47], v[212:215], v[8:11]
	v_mfma_f32_16x16x32_bf16 v[20:23], v[168:171], v[200:203], v[20:23]
	v_mfma_f32_16x16x32_bf16 v[16:19], v[176:179], v[200:203], v[16:19]
	v_mfma_f32_16x16x32_bf16 v[4:7], v[168:171], v[208:211], v[4:7]
	v_mfma_f32_16x16x32_bf16 v[0:3], v[176:179], v[208:211], v[0:3]
	v_mfma_f32_16x16x32_bf16 v[32:35], v[168:171], v[184:187], v[68:71]
	v_mfma_f32_16x16x32_bf16 v[36:39], v[176:179], v[184:187], v[64:67]
	v_mfma_f32_16x16x32_bf16 v[40:43], v[168:171], v[192:195], v[52:55]
	v_mfma_f32_16x16x32_bf16 v[44:47], v[176:179], v[192:195], v[48:51]
	v_mfma_f32_16x16x32_bf16 v[20:23], v[172:175], v[204:207], v[20:23]
	v_mfma_f32_16x16x32_bf16 v[16:19], v[180:183], v[204:207], v[16:19]
	v_mfma_f32_16x16x32_bf16 v[4:7], v[172:175], v[212:215], v[4:7]
	v_mfma_f32_16x16x32_bf16 v[0:3], v[180:183], v[212:215], v[0:3]
	v_mfma_f32_16x16x32_bf16 v[32:35], v[172:175], v[188:191], v[32:35]
	v_mfma_f32_16x16x32_bf16 v[36:39], v[180:183], v[188:191], v[36:39]
	v_mfma_f32_16x16x32_bf16 v[40:43], v[172:175], v[196:199], v[40:43]
	v_mfma_f32_16x16x32_bf16 v[44:47], v[180:183], v[196:199], v[44:47]
	s_barrier
	s_add_i32 s57, 0, 0x18000
	s_add_i32 s58, 0, 0x1c000
	v_add_u32_e32 v68, s57, v163
	v_add_u32_e32 v180, s58, v163
	ds_read_b128 v[48:51], v68
	ds_read_b128 v[52:55], v68 offset:1024
	ds_read_b128 v[64:67], v68 offset:2048
	ds_read_b128 v[68:71], v68 offset:3072
	ds_read_b128 v[168:171], v180
	ds_read_b128 v[172:175], v180 offset:1024
	ds_read_b128 v[176:179], v180 offset:2048
	ds_read_b128 v[180:183], v180 offset:3072
	s_add_u32 s20, s20, 0x40000
	s_addc_u32 s21, s21, 0
	s_mov_b32 m0, s71
	v_lshl_add_u64 v[222:223], s[20:21], 0, v[146:147]
	ds_read_b128 v[184:187], v167 offset:32768
	ds_read_b128 v[188:191], v167 offset:33792
	ds_read_b128 v[192:195], v167 offset:34816
	ds_read_b128 v[196:199], v167 offset:35840
	ds_read_b128 v[200:203], v167 offset:36864
	ds_read_b128 v[204:207], v167 offset:37888
	ds_read_b128 v[208:211], v167 offset:38912
	ds_read_b128 v[212:215], v167 offset:39936
	global_load_lds_dwordx4 v[222:223], off
	v_lshl_add_u64 v[222:223], s[20:21], 0, v[150:151]
	s_mov_b32 m0, s86
	s_nop 0
	global_load_lds_dwordx4 v[222:223], off
	s_waitcnt vmcnt(8)
	s_waitcnt lgkmcnt(0)
	s_barrier
	s_waitcnt lgkmcnt(0)
	v_mfma_f32_16x16x32_bf16 v[142:145], v[48:51], v[184:187], v[142:145]
	v_mfma_f32_16x16x32_bf16 v[138:141], v[64:67], v[184:187], v[138:141]
	v_mfma_f32_16x16x32_bf16 v[124:127], v[48:51], v[192:195], v[124:127]
	v_mfma_f32_16x16x32_bf16 v[120:123], v[64:67], v[192:195], v[120:123]
	v_mfma_f32_16x16x32_bf16 v[108:111], v[48:51], v[200:203], v[108:111]
	v_mfma_f32_16x16x32_bf16 v[104:107], v[64:67], v[200:203], v[104:107]
	v_mfma_f32_16x16x32_bf16 v[92:95], v[48:51], v[208:211], v[92:95]
	v_mfma_f32_16x16x32_bf16 v[88:91], v[64:67], v[208:211], v[88:91]
	v_mfma_f32_16x16x32_bf16 v[142:145], v[52:55], v[188:191], v[142:145]
	v_mfma_f32_16x16x32_bf16 v[138:141], v[68:71], v[188:191], v[138:141]
	v_mfma_f32_16x16x32_bf16 v[124:127], v[52:55], v[196:199], v[124:127]
	v_mfma_f32_16x16x32_bf16 v[120:123], v[68:71], v[196:199], v[120:123]
	v_mfma_f32_16x16x32_bf16 v[108:111], v[52:55], v[204:207], v[108:111]
	v_mfma_f32_16x16x32_bf16 v[104:107], v[68:71], v[204:207], v[104:107]
	v_mfma_f32_16x16x32_bf16 v[92:95], v[52:55], v[212:215], v[92:95]
	v_mfma_f32_16x16x32_bf16 v[88:91], v[68:71], v[212:215], v[88:91]
	v_mfma_f32_16x16x32_bf16 v[134:137], v[168:171], v[184:187], v[134:137]
	v_mfma_f32_16x16x32_bf16 v[130:133], v[176:179], v[184:187], v[130:133]
	v_mfma_f32_16x16x32_bf16 v[116:119], v[168:171], v[192:195], v[116:119]
	v_mfma_f32_16x16x32_bf16 v[112:115], v[176:179], v[192:195], v[112:115]
	v_mfma_f32_16x16x32_bf16 v[100:103], v[168:171], v[200:203], v[100:103]
	v_mfma_f32_16x16x32_bf16 v[96:99], v[176:179], v[200:203], v[96:99]
	v_mfma_f32_16x16x32_bf16 v[84:87], v[168:171], v[208:211], v[84:87]
	v_mfma_f32_16x16x32_bf16 v[80:83], v[176:179], v[208:211], v[80:83]
	v_mfma_f32_16x16x32_bf16 v[134:137], v[172:175], v[188:191], v[134:137]
	v_mfma_f32_16x16x32_bf16 v[130:133], v[180:183], v[188:191], v[130:133]
	v_mfma_f32_16x16x32_bf16 v[116:119], v[172:175], v[196:199], v[116:119]
	v_mfma_f32_16x16x32_bf16 v[112:115], v[180:183], v[196:199], v[112:115]
	v_mfma_f32_16x16x32_bf16 v[100:103], v[172:175], v[204:207], v[100:103]
	v_mfma_f32_16x16x32_bf16 v[96:99], v[180:183], v[204:207], v[96:99]
	v_mfma_f32_16x16x32_bf16 v[84:87], v[172:175], v[212:215], v[84:87]
	v_mfma_f32_16x16x32_bf16 v[80:83], v[180:183], v[212:215], v[80:83]
	s_barrier
; #define PG8_STAGE(bufoff, gbase, voff) do { _Pragma("unroll") for (int _i = 0; _i < 2; ++_i) \
;         __builtin_amdgcn_global_load_lds((const unsigned*)((const char*)(gbase) + (voff)[_i]), (LAS unsigned*)(lds + (bufoff) + ldsw + _i * 8192), 16, 0, 0); } while (0)
; #define PG8_LDA(dst, b, h) do { _Pragma("unroll") for (int m = 0; m < 4; ++m) _Pragma("unroll") for (int k = 0; k < 2; ++k) dst[m][k] = *(const LAS bf16x8*)(lds + PG8_SA(b, h) + aoff + m * 2048 + k * 1024); } while (0)
; #define PG8_MMA(ai, bj, At, Bt) do { __builtin_amdgcn_s_setprio(1); _Pragma("unroll") for (int m = 0; m < 4; ++m) _Pragma("unroll") for (int n = 0; n < 2; ++n) _Pragma("unroll") for (int k = 0; k < 2; ++k) \
;         acc[ai][bj][m][n] = __builtin_amdgcn_mfma_f32_16x16x32_bf16(Bt[n][k], At[m][k], acc[ai][bj][m][n], 0, 0, 0); __builtin_amdgcn_s_setprio(0); } while (0)
; #define PG8_WAIT_V(n) asm volatile("s_waitcnt vmcnt(" #n ")" ::: "memory")
; #define PG8_WAIT_L(n) asm volatile("s_waitcnt lgkmcnt(" #n ")" ::: "memory")
; #define PG8_BAR __builtin_amdgcn_s_barrier()
; #define PG8_SCHED __builtin_amdgcn_sched_barrier(0)
; template <class Epi>
; __device__ __forceinline__ void gemm_phase(LAS unsigned char* lds, const Gemm g, const StaticOrder& S, const Epi& E, const int tid_in) {
;     ...
;             PG8_LDA(At, 1, 1); PG8_STAGE(PG8_SB(1, 0), b3, voffB); PG8_STAGE(PG8_SB(1, 1), b3 + hstepB, voffB); PG8_STAGE(PG8_SA(1, 0), a3, voffA);
;             PG8_WAIT_V(8); PG8_WAIT_L(0); PG8_BAR; PG8_MMA(1, 0, At, B0); PG8_MMA(1, 1, At, B1); PG8_BAR; PG8_SCHED;
;         }
;         if (wr == 0) PG8_BAR;
	s_add_i32 s20, s57, s45
	v_lshl_add_u64 v[160:161], v[160:161], 0, s[54:55]
	s_mov_b32 m0, s20
	ds_read_b128 v[184:187], v167 offset:49152
	ds_read_b128 v[188:191], v167 offset:50176
	ds_read_b128 v[192:195], v167 offset:51200
	ds_read_b128 v[196:199], v167 offset:52224
	ds_read_b128 v[200:203], v167 offset:53248
	ds_read_b128 v[204:207], v167 offset:54272
	ds_read_b128 v[208:211], v167 offset:55296
	ds_read_b128 v[212:215], v167 offset:56320
	global_load_lds_dwordx4 v[160:161], off
	s_add_i32 m0, s20, 0x2000
	s_add_u32 s20, s34, 0x40080
	v_lshl_add_u64 v[160:161], v[216:217], 0, s[54:55]
	s_addc_u32 s21, s35, 0
	s_add_i32 s34, s58, s45
	global_load_lds_dwordx4 v[160:161], off
	v_lshl_add_u64 v[160:161], s[20:21], 0, v[148:149]
	s_mov_b32 m0, s34
	s_nop 0
	global_load_lds_dwordx4 v[160:161], off
	v_lshl_add_u64 v[160:161], s[20:21], 0, v[152:153]
	s_add_i32 m0, s34, 0x2000
	s_nop 0
	global_load_lds_dwordx4 v[160:161], off
	v_lshl_add_u64 v[160:161], v[218:219], 0, s[54:55]
	s_mov_b32 m0, s88
	s_nop 0
	global_load_lds_dwordx4 v[160:161], off
	v_lshl_add_u64 v[160:161], v[220:221], 0, s[54:55]
	s_mov_b32 m0, s89
	s_nop 0
	global_load_lds_dwordx4 v[160:161], off
	s_waitcnt vmcnt(8)
	s_waitcnt lgkmcnt(0)
	s_barrier
	s_waitcnt lgkmcnt(0)
	v_mfma_f32_16x16x32_bf16 v[76:79], v[48:51], v[184:187], v[76:79]
	v_mfma_f32_16x16x32_bf16 v[72:75], v[64:67], v[184:187], v[72:75]
	v_mfma_f32_16x16x32_bf16 v[60:63], v[48:51], v[192:195], v[60:63]
	v_mfma_f32_16x16x32_bf16 v[56:59], v[64:67], v[192:195], v[56:59]
	v_mfma_f32_16x16x32_bf16 v[28:31], v[48:51], v[200:203], v[28:31]
	v_mfma_f32_16x16x32_bf16 v[24:27], v[64:67], v[200:203], v[24:27]
	v_mfma_f32_16x16x32_bf16 v[12:15], v[48:51], v[208:211], v[12:15]
	v_mfma_f32_16x16x32_bf16 v[8:11], v[64:67], v[208:211], v[8:11]
	v_mfma_f32_16x16x32_bf16 v[76:79], v[52:55], v[188:191], v[76:79]
	v_mfma_f32_16x16x32_bf16 v[72:75], v[68:71], v[188:191], v[72:75]
	v_mfma_f32_16x16x32_bf16 v[60:63], v[52:55], v[196:199], v[60:63]
	v_mfma_f32_16x16x32_bf16 v[56:59], v[68:71], v[196:199], v[56:59]
	v_mfma_f32_16x16x32_bf16 v[28:31], v[52:55], v[204:207], v[28:31]
	v_mfma_f32_16x16x32_bf16 v[24:27], v[68:71], v[204:207], v[24:27]
	v_mfma_f32_16x16x32_bf16 v[12:15], v[52:55], v[212:215], v[12:15]
	v_mfma_f32_16x16x32_bf16 v[8:11], v[68:71], v[212:215], v[8:11]
	v_mfma_f32_16x16x32_bf16 v[32:35], v[168:171], v[184:187], v[32:35]
	v_mfma_f32_16x16x32_bf16 v[68:71], v[172:175], v[188:191], v[32:35]
	v_mfma_f32_16x16x32_bf16 v[32:35], v[176:179], v[184:187], v[36:39]
	v_mfma_f32_16x16x32_bf16 v[64:67], v[180:183], v[188:191], v[32:35]
	v_mfma_f32_16x16x32_bf16 v[32:35], v[168:171], v[192:195], v[40:43]
	v_mfma_f32_16x16x32_bf16 v[52:55], v[172:175], v[196:199], v[32:35]
	v_mfma_f32_16x16x32_bf16 v[32:35], v[176:179], v[192:195], v[44:47]
	v_mfma_f32_16x16x32_bf16 v[20:23], v[168:171], v[200:203], v[20:23]
	v_mfma_f32_16x16x32_bf16 v[16:19], v[176:179], v[200:203], v[16:19]
	v_mfma_f32_16x16x32_bf16 v[4:7], v[168:171], v[208:211], v[4:7]
	v_mfma_f32_16x16x32_bf16 v[0:3], v[176:179], v[208:211], v[0:3]
	v_mfma_f32_16x16x32_bf16 v[48:51], v[180:183], v[196:199], v[32:35]
	v_mfma_f32_16x16x32_bf16 v[20:23], v[172:175], v[204:207], v[20:23]
	v_mfma_f32_16x16x32_bf16 v[16:19], v[180:183], v[204:207], v[16:19]
	v_mfma_f32_16x16x32_bf16 v[4:7], v[172:175], v[212:215], v[4:7]
	v_mfma_f32_16x16x32_bf16 v[0:3], v[180:183], v[212:215], v[0:3]
	s_barrier
	s_add_i32 s56, s56, 2
	s_add_u32 s36, s36, 0x100
	s_addc_u32 s37, s37, 0
	s_add_u32 s38, s38, 0x100
	s_addc_u32 s39, s39, 0
	s_cmp_gt_u32 s56, 13
	s_cbranch_scc0 .LBB0_232
	s_and_b64 vcc, exec, s[28:29]
	s_cbranch_vccz .LBB0_235
	s_barrier
